# layer-1 w_in int8 strips converted in phase 0 by workgroups 68..135 instead of GEMM1 tail of layer 0 (on top of strip rewrite)
# speedup vs baseline: 1.1358x; 1.0101x over previous
; #define BIDX opqs((int)blockIdx.x)
; __device__ __forceinline__ void convert_strip(const Ctx& c, float* scr, int l, int s) {
;     if (s < 64) { const int n = s >> 4, cs = (s & 15) * 64;
;         convert_i8_strip(c.w_gate + (size_t)(l * 4 + n) * DM * DM + cs, DM, c.Wg8 + ((size_t)l * 4096 + n * 1024 + cs) * DM, c.SW + (size_t)l * 4096 + n * 1024 + cs, scr, 1, 0); }
;     else { const int cs = (s - 64) * 64;
;         const int rmul = (cs >= ZB && cs < ZQ) ? 2 : 1, radd = (cs >= ZB && cs < ZB + 256) ? cs - ZB : ((cs >= ZB + 256 && cs < ZQ) ? cs - ZB - 511 : 0);
;         convert_i8_strip(c.w_in + (size_t)l * DM * DIN + cs, DIN, c.Win8 + ((size_t)l * DIN + cs) * DM, c.SWI + (size_t)l * DIN + cs, scr, rmul, radd); }
; __device__ __forceinline__ void phase_pre(const Ctx& c, float* lds) {
;     for (int s_ = BIDX; s_ < DIN / 64; s_ += gridDim.x) convert_strip(c, lds, 0, 64 + s_);
.LBB0_5:
	s_or_b64 exec, exec, s[0:1]
	s_cmp_lt_i32 s86, 1
	s_cselect_b64 s[0:1], -1, 0
	s_cmp_gt_i32 s87, 0
	s_cselect_b64 s[2:3], -1, 0
	s_and_b64 s[0:1], s[0:1], s[2:3]
	s_andn2_b64 vcc, exec, s[0:1]
	s_cbranch_vccnz .LBB0_123
	v_readlane_b32 s2, v255, 0
	v_readlane_b32 s3, v255, 1
	s_mov_b64 s[0:1], s[2:3]
	s_load_dwordx4 s[8:11], s[0:1], 0x0
	s_load_dwordx2 s[4:5], s[0:1], 0x10
	s_load_dwordx2 s[6:7], s[0:1], 0x88
	s_add_u32 s12, s2, 0x98
	s_mov_b32 s26, s88
	s_addc_u32 s13, s3, 0
	s_cmpk_gt_i32 s26, 0x87
	s_cbranch_scc1 .LBB0_30
	s_waitcnt lgkmcnt(0)
	s_add_u32 s27, s6, 0x1dd28000
	s_addc_u32 s28, s7, 0
	s_add_u32 s29, s6, 0x1dd30000
	s_load_dwordx2 s[14:15], s[0:1], 0x60
	s_addc_u32 s30, s7, 0
	s_add_u32 s16, s6, 0x890000
	s_addc_u32 s17, s7, 0
	s_add_u32 s18, s6, 0x1110000
	s_addc_u32 s19, s7, 0
	s_mov_b32 s21, 0
	v_mov_b32_e32 v3, 0
	s_movk_i32 s31, 0x4400
	s_mov_b32 s33, 0x42fe0000
	s_movk_i32 s34, 0x104
	s_mov_b32 s35, 0xc0c0500
	s_branch .LBB0_9
.LBB0_8:
	s_load_dword s0, s[12:13], 0x0
	s_waitcnt lgkmcnt(0)
	s_add_i32 s26, s0, s26
	s_cmpk_gt_i32 s26, 0x87
	s_cbranch_scc1 .LBB0_30
.LBB0_9:
.Lns_p0:
	s_add_u32 s61, s26, 64
	s_sub_u32 s75, s26, 4
	s_cmp_lt_u32 s26, 68
	s_cselect_b32 s60, 0, 1
	s_cselect_b32 s61, s61, s75
	s_barrier
	v_readlane_b32 s62, v255, 0
	v_readlane_b32 s63, v255, 1
	s_load_dwordx2 s[64:65], s[62:63], 0x10
	s_load_dwordx2 s[66:67], s[62:63], 0x60
	s_load_dwordx2 s[68:69], s[62:63], 0x88
	s_mov_b32 s81, 0
	s_mov_b32 s82, 0
	s_cmp_lt_u32 s61, 64
	s_cbranch_scc0 .Lns_p0_win
	s_lshr_b32 s70, s61, 4
	s_and_b32 s71, s61, 15
	s_lshl_b32 s71, s71, 6
	s_lshl_b32 s72, s60, 2
	s_add_u32 s72, s72, s70
	s_lshl_b32 s73, s72, 10
	s_add_u32 s73, s73, s71
	s_lshl_b32 s74, s72, 22
	s_lshl_b32 s75, s71, 2
	s_add_u32 s74, s74, s75
	s_waitcnt lgkmcnt(0)
	s_add_u32 s76, s66, s74
	s_addc_u32 s77, s67, 0
	s_movk_i32 s78, 0x1000
	s_mov_b32 s79, 0x1110000
	s_mov_b32 s80, 0x1dd28000
	s_branch .Lns_p0_go

; #define TIDX opq((int)threadIdx.x)
; __device__ __forceinline__ void convert_i8_strip(const float* W, int ldw, signed char* WT, float* SWp, float* scr, int rmul, int radd) {
;     const int t = TIDX, kg = t >> 6, nn = t & 63;
;     float am = 0.f;
; #pragma unroll 1
;     for (int i0 = 0; i0 < 128; i0 += 64) {
;         float v[64];
; #pragma unroll
;         for (int i = 0; i < 64; ++i) v[i] = W[(size_t)(kg + 8 * (i0 + i)) * ldw + nn];
; #pragma unroll
;         for (int i = 0; i < 64; ++i) am = fmaxf(am, fabsf(v[i]));
;     }
.Lns_p0_go:
	s_add_u32 s73, s73, s82
	s_lshl_b32 s74, s73, 10
	s_add_u32 s74, s74, s79
	s_add_u32 s70, s68, s74
	s_addc_u32 s71, s69, 0
	s_lshl_b32 s74, s73, 2
	s_add_u32 s74, s74, s80
	s_add_u32 s72, s68, s74
	s_addc_u32 s73, s69, 0
	v_and_b32_e32 v89, 15, v0
	v_lshrrev_b32_e32 v91, 4, v0
	v_lshlrev_b32_e32 v91, 5, v91
	v_lshlrev_b32_e32 v88, 4, v0
	v_mul_lo_u32 v90, v91, s78
	v_lshl_add_u32 v90, v89, 4, v90
	s_add_u32 s74, s81, 12
	v_lshlrev_b32_e32 v248, s74, v89
	v_add_u32_e32 v248, v248, v91
	s_lshl_b32 s75, 0x400, s81
	v_add_u32_e32 v249, s75, v248
	s_lshl_b32 s75, 0x800, s81
	v_add_u32_e32 v250, s75, v248
	s_lshl_b32 s75, 0xc00, s81
	v_add_u32_e32 v251, s75, v248
	s_add_u32 s82, s76, s78
	s_addc_u32 s83, s77, 0
	global_load_dwordx4 v[96:99], v90, s[76:77]
	s_add_u32 s76, s76, s78
	s_addc_u32 s77, s77, 0
	s_add_u32 s76, s76, s78
	s_addc_u32 s77, s77, 0
	global_load_dwordx4 v[100:103], v90, s[82:83]
	s_add_u32 s82, s82, s78
	s_addc_u32 s83, s83, 0
	s_add_u32 s82, s82, s78
	s_addc_u32 s83, s83, 0
	global_load_dwordx4 v[104:107], v90, s[76:77]
	s_add_u32 s76, s76, s78
	s_addc_u32 s77, s77, 0
	s_add_u32 s76, s76, s78
	s_addc_u32 s77, s77, 0
	global_load_dwordx4 v[108:111], v90, s[82:83]
	s_add_u32 s82, s82, s78
	s_addc_u32 s83, s83, 0
	s_add_u32 s82, s82, s78
	s_addc_u32 s83, s83, 0
	global_load_dwordx4 v[112:115], v90, s[76:77]
	s_add_u32 s76, s76, s78
	s_addc_u32 s77, s77, 0
	s_add_u32 s76, s76, s78
	s_addc_u32 s77, s77, 0
	global_load_dwordx4 v[116:119], v90, s[82:83]
	s_add_u32 s82, s82, s78
	s_addc_u32 s83, s83, 0
	s_add_u32 s82, s82, s78
	s_addc_u32 s83, s83, 0
	global_load_dwordx4 v[120:123], v90, s[76:77]
	s_add_u32 s76, s76, s78
	s_addc_u32 s77, s77, 0
	s_add_u32 s76, s76, s78
	s_addc_u32 s77, s77, 0
	global_load_dwordx4 v[124:127], v90, s[82:83]
	s_add_u32 s82, s82, s78
	s_addc_u32 s83, s83, 0
	s_add_u32 s82, s82, s78
	s_addc_u32 s83, s83, 0
	global_load_dwordx4 v[128:131], v90, s[76:77]
	s_add_u32 s76, s76, s78
	s_addc_u32 s77, s77, 0
	s_add_u32 s76, s76, s78
	s_addc_u32 s77, s77, 0
	global_load_dwordx4 v[132:135], v90, s[82:83]
	s_add_u32 s82, s82, s78
	s_addc_u32 s83, s83, 0
	s_add_u32 s82, s82, s78
	s_addc_u32 s83, s83, 0
	global_load_dwordx4 v[136:139], v90, s[76:77]
	s_add_u32 s76, s76, s78
	s_addc_u32 s77, s77, 0
	s_add_u32 s76, s76, s78
	s_addc_u32 s77, s77, 0
	global_load_dwordx4 v[140:143], v90, s[82:83]
	s_add_u32 s82, s82, s78
	s_addc_u32 s83, s83, 0
	s_add_u32 s82, s82, s78
	s_addc_u32 s83, s83, 0
	global_load_dwordx4 v[144:147], v90, s[76:77]
	s_add_u32 s76, s76, s78
	s_addc_u32 s77, s77, 0
	s_add_u32 s76, s76, s78
	s_addc_u32 s77, s77, 0
	global_load_dwordx4 v[148:151], v90, s[82:83]
	s_add_u32 s82, s82, s78
	s_addc_u32 s83, s83, 0
	s_add_u32 s82, s82, s78
	s_addc_u32 s83, s83, 0
	global_load_dwordx4 v[152:155], v90, s[76:77]
	s_add_u32 s76, s76, s78
	s_addc_u32 s77, s77, 0
	s_add_u32 s76, s76, s78
	s_addc_u32 s77, s77, 0
	global_load_dwordx4 v[156:159], v90, s[82:83]
	s_add_u32 s82, s82, s78
	s_addc_u32 s83, s83, 0
	s_add_u32 s82, s82, s78
	s_addc_u32 s83, s83, 0
	global_load_dwordx4 v[160:163], v90, s[76:77]
	s_add_u32 s76, s76, s78
	s_addc_u32 s77, s77, 0
	s_add_u32 s76, s76, s78
	s_addc_u32 s77, s77, 0
	global_load_dwordx4 v[164:167], v90, s[82:83]
	s_add_u32 s82, s82, s78
	s_addc_u32 s83, s83, 0
	s_add_u32 s82, s82, s78
	s_addc_u32 s83, s83, 0
	global_load_dwordx4 v[168:171], v90, s[76:77]
	s_add_u32 s76, s76, s78
	s_addc_u32 s77, s77, 0
	s_add_u32 s76, s76, s78
	s_addc_u32 s77, s77, 0
	global_load_dwordx4 v[172:175], v90, s[82:83]
	s_add_u32 s82, s82, s78
	s_addc_u32 s83, s83, 0
	s_add_u32 s82, s82, s78
	s_addc_u32 s83, s83, 0
	global_load_dwordx4 v[176:179], v90, s[76:77]
	s_add_u32 s76, s76, s78
	s_addc_u32 s77, s77, 0
	s_add_u32 s76, s76, s78
	s_addc_u32 s77, s77, 0
	global_load_dwordx4 v[180:183], v90, s[82:83]
	s_add_u32 s82, s82, s78
	s_addc_u32 s83, s83, 0
	s_add_u32 s82, s82, s78
	s_addc_u32 s83, s83, 0
	global_load_dwordx4 v[184:187], v90, s[76:77]
	s_add_u32 s76, s76, s78
	s_addc_u32 s77, s77, 0
	s_add_u32 s76, s76, s78
	s_addc_u32 s77, s77, 0
	global_load_dwordx4 v[188:191], v90, s[82:83]
	s_add_u32 s82, s82, s78
	s_addc_u32 s83, s83, 0
	s_add_u32 s82, s82, s78
	s_addc_u32 s83, s83, 0
	global_load_dwordx4 v[192:195], v90, s[76:77]
	s_add_u32 s76, s76, s78
	s_addc_u32 s77, s77, 0
	s_add_u32 s76, s76, s78
	s_addc_u32 s77, s77, 0
	global_load_dwordx4 v[196:199], v90, s[82:83]
	s_add_u32 s82, s82, s78
	s_addc_u32 s83, s83, 0
	s_add_u32 s82, s82, s78
	s_addc_u32 s83, s83, 0
	global_load_dwordx4 v[200:203], v90, s[76:77]
	s_add_u32 s76, s76, s78
	s_addc_u32 s77, s77, 0
	s_add_u32 s76, s76, s78
	s_addc_u32 s77, s77, 0
	global_load_dwordx4 v[204:207], v90, s[82:83]
	s_add_u32 s82, s82, s78
	s_addc_u32 s83, s83, 0
	s_add_u32 s82, s82, s78
	s_addc_u32 s83, s83, 0
	global_load_dwordx4 v[208:211], v90, s[76:77]
	s_add_u32 s76, s76, s78
	s_addc_u32 s77, s77, 0
	s_add_u32 s76, s76, s78
	s_addc_u32 s77, s77, 0
	global_load_dwordx4 v[212:215], v90, s[82:83]
	s_add_u32 s82, s82, s78
	s_addc_u32 s83, s83, 0
	s_add_u32 s82, s82, s78
	s_addc_u32 s83, s83, 0
	global_load_dwordx4 v[216:219], v90, s[76:77]
	global_load_dwordx4 v[220:223], v90, s[82:83]
	v_lshlrev_b32_e32 v89, 4, v89
	s_mov_b32 s98, 0x0c0c0400
	s_waitcnt vmcnt(29)
	v_max3_f32 v92, |v96|, |v100|, |v104|
	v_max3_f32 v93, |v97|, |v101|, |v105|
	v_max3_f32 v94, |v98|, |v102|, |v106|
	v_max3_f32 v95, |v99|, |v103|, |v107|
	s_waitcnt vmcnt(27)
	v_max3_f32 v92, v92, |v108|, |v112|
	v_max3_f32 v93, v93, |v109|, |v113|
	v_max3_f32 v94, v94, |v110|, |v114|
	v_max3_f32 v95, v95, |v111|, |v115|
	s_waitcnt vmcnt(25)
; __device__ __forceinline__ void convert_i8_strip(const float* W, int ldw, signed char* WT, float* SWp, float* scr, int rmul, int radd) {
;     ...
;         for (int i = 0; i < 64; ++i) am = fmaxf(am, fabsf(v[i]));
;     }
;     scr[kg * 64 + nn] = am;
;     __syncthreads();
;     if (t < 64) { float m = scr[t];
; #pragma unroll
;         for (int k = 1; k < 8; ++k) m = fmaxf(m, scr[k * 64 + t]);
;         scr[512 + t] = m; SWp[rmul * t + radd] = m * (1.f / 127.f); }
;     __syncthreads();
;     const float cm = scr[512 + nn], inv = cm > 0.f ? 127.f / cm : 0.f;
	v_max3_f32 v92, v92, |v116|, |v120|
	v_max3_f32 v93, v93, |v117|, |v121|
	v_max3_f32 v94, v94, |v118|, |v122|
	v_max3_f32 v95, v95, |v119|, |v123|
	s_waitcnt vmcnt(23)
	v_max3_f32 v92, v92, |v124|, |v128|
	v_max3_f32 v93, v93, |v125|, |v129|
	v_max3_f32 v94, v94, |v126|, |v130|
	v_max3_f32 v95, v95, |v127|, |v131|
	s_waitcnt vmcnt(21)
	v_max3_f32 v92, v92, |v132|, |v136|
	v_max3_f32 v93, v93, |v133|, |v137|
	v_max3_f32 v94, v94, |v134|, |v138|
	v_max3_f32 v95, v95, |v135|, |v139|
	s_waitcnt vmcnt(19)
	v_max3_f32 v92, v92, |v140|, |v144|
	v_max3_f32 v93, v93, |v141|, |v145|
	v_max3_f32 v94, v94, |v142|, |v146|
	v_max3_f32 v95, v95, |v143|, |v147|
	s_waitcnt vmcnt(17)
	v_max3_f32 v92, v92, |v148|, |v152|
	v_max3_f32 v93, v93, |v149|, |v153|
	v_max3_f32 v94, v94, |v150|, |v154|
	v_max3_f32 v95, v95, |v151|, |v155|
	s_waitcnt vmcnt(15)
	v_max3_f32 v92, v92, |v156|, |v160|
	v_max3_f32 v93, v93, |v157|, |v161|
	v_max3_f32 v94, v94, |v158|, |v162|
	v_max3_f32 v95, v95, |v159|, |v163|
	s_waitcnt vmcnt(13)
	v_max3_f32 v92, v92, |v164|, |v168|
	v_max3_f32 v93, v93, |v165|, |v169|
	v_max3_f32 v94, v94, |v166|, |v170|
	v_max3_f32 v95, v95, |v167|, |v171|
	s_waitcnt vmcnt(11)
	v_max3_f32 v92, v92, |v172|, |v176|
	v_max3_f32 v93, v93, |v173|, |v177|
	v_max3_f32 v94, v94, |v174|, |v178|
	v_max3_f32 v95, v95, |v175|, |v179|
	s_waitcnt vmcnt(9)
	v_max3_f32 v92, v92, |v180|, |v184|
	v_max3_f32 v93, v93, |v181|, |v185|
	v_max3_f32 v94, v94, |v182|, |v186|
	v_max3_f32 v95, v95, |v183|, |v187|
	s_waitcnt vmcnt(7)
	v_max3_f32 v92, v92, |v188|, |v192|
	v_max3_f32 v93, v93, |v189|, |v193|
	v_max3_f32 v94, v94, |v190|, |v194|
	v_max3_f32 v95, v95, |v191|, |v195|
	s_waitcnt vmcnt(5)
	v_max3_f32 v92, v92, |v196|, |v200|
	v_max3_f32 v93, v93, |v197|, |v201|
	v_max3_f32 v94, v94, |v198|, |v202|
	v_max3_f32 v95, v95, |v199|, |v203|
	s_waitcnt vmcnt(3)
	v_max3_f32 v92, v92, |v204|, |v208|
	v_max3_f32 v93, v93, |v205|, |v209|
	v_max3_f32 v94, v94, |v206|, |v210|
	v_max3_f32 v95, v95, |v207|, |v211|
	s_waitcnt vmcnt(1)
	v_max3_f32 v92, v92, |v212|, |v216|
	v_max3_f32 v93, v93, |v213|, |v217|
	v_max3_f32 v94, v94, |v214|, |v218|
	v_max3_f32 v95, v95, |v215|, |v219|
	s_waitcnt vmcnt(0)
	v_max_f32_e64 v92, v92, |v220|
	v_max_f32_e64 v93, v93, |v221|
	v_max_f32_e64 v94, v94, |v222|
	v_max_f32_e64 v95, v95, |v223|
	ds_write_b128 v88, v[92:95]
	s_waitcnt lgkmcnt(0)
	s_barrier
	ds_read_b128 v[224:227], v89 offset:0
	ds_read_b128 v[228:231], v89 offset:256
	ds_read_b128 v[232:235], v89 offset:512
	ds_read_b128 v[236:239], v89 offset:768
	s_waitcnt lgkmcnt(0)
	v_max3_f32 v92, v224, v228, v232
	v_max_f32_e32 v92, v92, v236
	v_max3_f32 v93, v225, v229, v233
	v_max_f32_e32 v93, v93, v237
	v_max3_f32 v94, v226, v230, v234
	v_max_f32_e32 v94, v94, v238
	v_max3_f32 v95, v227, v231, v235
	v_max_f32_e32 v95, v95, v239
	ds_read_b128 v[224:227], v89 offset:1024
	ds_read_b128 v[228:231], v89 offset:1280
	ds_read_b128 v[232:235], v89 offset:1536
	ds_read_b128 v[236:239], v89 offset:1792
	s_waitcnt lgkmcnt(0)
	v_max3_f32 v92, v92, v224, v228
	v_max3_f32 v92, v92, v232, v236
	v_max3_f32 v93, v93, v225, v229
	v_max3_f32 v93, v93, v233, v237
	v_max3_f32 v94, v94, v226, v230
	v_max3_f32 v94, v94, v234, v238
	v_max3_f32 v95, v95, v227, v231
	v_max3_f32 v95, v95, v235, v239
	ds_read_b128 v[224:227], v89 offset:2048
	ds_read_b128 v[228:231], v89 offset:2304
	ds_read_b128 v[232:235], v89 offset:2560
	ds_read_b128 v[236:239], v89 offset:2816
	s_waitcnt lgkmcnt(0)
	v_max3_f32 v92, v92, v224, v228
	v_max3_f32 v92, v92, v232, v236
	v_max3_f32 v93, v93, v225, v229
	v_max3_f32 v93, v93, v233, v237
	v_max3_f32 v94, v94, v226, v230
	v_max3_f32 v94, v94, v234, v238
	v_max3_f32 v95, v95, v227, v231
	v_max3_f32 v95, v95, v235, v239
	ds_read_b128 v[224:227], v89 offset:3072
	ds_read_b128 v[228:231], v89 offset:3328
	ds_read_b128 v[232:235], v89 offset:3584
	ds_read_b128 v[236:239], v89 offset:3840
	s_waitcnt lgkmcnt(0)
	v_max3_f32 v92, v92, v224, v228
	v_max3_f32 v92, v92, v232, v236
	v_max3_f32 v93, v93, v225, v229
	v_max3_f32 v93, v93, v233, v237
	v_max3_f32 v94, v94, v226, v230
	v_max3_f32 v94, v94, v234, v238
	v_max3_f32 v95, v95, v227, v231
	v_max3_f32 v95, v95, v235, v239
	ds_read_b128 v[224:227], v89 offset:4096
	ds_read_b128 v[228:231], v89 offset:4352
	ds_read_b128 v[232:235], v89 offset:4608
	ds_read_b128 v[236:239], v89 offset:4864
	s_waitcnt lgkmcnt(0)
	v_max3_f32 v92, v92, v224, v228
	v_max3_f32 v92, v92, v232, v236
	v_max3_f32 v93, v93, v225, v229
	v_max3_f32 v93, v93, v233, v237
	v_max3_f32 v94, v94, v226, v230
	v_max3_f32 v94, v94, v234, v238
	v_max3_f32 v95, v95, v227, v231
	v_max3_f32 v95, v95, v235, v239
	ds_read_b128 v[224:227], v89 offset:5120
	ds_read_b128 v[228:231], v89 offset:5376
	ds_read_b128 v[232:235], v89 offset:5632
	ds_read_b128 v[236:239], v89 offset:5888
	s_waitcnt lgkmcnt(0)
	v_max3_f32 v92, v92, v224, v228
	v_max3_f32 v92, v92, v232, v236
	v_max3_f32 v93, v93, v225, v229
	v_max3_f32 v93, v93, v233, v237
	v_max3_f32 v94, v94, v226, v230
	v_max3_f32 v94, v94, v234, v238
	v_max3_f32 v95, v95, v227, v231
	v_max3_f32 v95, v95, v235, v239
	ds_read_b128 v[224:227], v89 offset:6144
	ds_read_b128 v[228:231], v89 offset:6400
	ds_read_b128 v[232:235], v89 offset:6656
	ds_read_b128 v[236:239], v89 offset:6912
	s_waitcnt lgkmcnt(0)
	v_max3_f32 v92, v92, v224, v228
	v_max3_f32 v92, v92, v232, v236
	v_max3_f32 v93, v93, v225, v229
	v_max3_f32 v93, v93, v233, v237
	v_max3_f32 v94, v94, v226, v230
	v_max3_f32 v94, v94, v234, v238
	v_max3_f32 v95, v95, v227, v231
	v_max3_f32 v95, v95, v235, v239
	ds_read_b128 v[224:227], v89 offset:7168
	ds_read_b128 v[228:231], v89 offset:7424
	ds_read_b128 v[232:235], v89 offset:7680
	ds_read_b128 v[236:239], v89 offset:7936
	s_waitcnt lgkmcnt(0)
	v_max3_f32 v92, v92, v224, v228
	v_max3_f32 v92, v92, v232, v236
	v_max3_f32 v93, v93, v225, v229
	v_max3_f32 v93, v93, v233, v237
	v_max3_f32 v94, v94, v226, v230
	v_max3_f32 v94, v94, v234, v238
	v_max3_f32 v95, v95, v227, v231
	v_max3_f32 v95, v95, v235, v239
	s_barrier
; __device__ __forceinline__ void convert_i8_strip(const float* W, int ldw, signed char* WT, float* SWp, float* scr, int rmul, int radd) {
;     ...
;     if (t < 64) { float m = scr[t];
; #pragma unroll
;         for (int k = 1; k < 8; ++k) m = fmaxf(m, scr[k * 64 + t]);
;         scr[512 + t] = m; SWp[rmul * t + radd] = m * (1.f / 127.f); }
;     __syncthreads();
;     const float cm = scr[512 + nn], inv = cm > 0.f ? 127.f / cm : 0.f;
;     __syncthreads();
;     float r[8];
; #pragma unroll
;     for (int i = 0; i < 8; ++i) r[i] = W[(size_t)(kg + 8 * i) * ldw + nn];
; #pragma unroll 1
;     for (int kb = 0; kb < 16; ++kb) {
; #pragma unroll
;         for (int i = 0; i < 8; ++i) scr[1024 + (kg + 8 * i) * 65 + nn] = r[i] * inv + 12582912.0f;
;         __syncthreads();
;         if (kb + 1 < 16) {
; #pragma unroll
;             for (int i = 0; i < 8; ++i) r[i] = W[(size_t)((kb + 1) * 64 + kg + 8 * i) * ldw + nn]; }
;         { const int on = t >> 3, kc = t & 7;
;           const unsigned* sp = (const unsigned*)(scr + 1024 + (8 * kc) * 65 + on);
;           u32x2 o; o.x = (sp[0] & 0xffu) | ((sp[65] & 0xffu) << 8) | ((sp[2 * 65] & 0xffu) << 16) | (sp[3 * 65] << 24);
;           o.y = (sp[4 * 65] & 0xffu) | ((sp[5 * 65] & 0xffu) << 8) | ((sp[6 * 65] & 0xffu) << 16) | (sp[7 * 65] << 24);
;           *(u32x2*)(WT + (ptrdiff_t)(rmul * on + radd) * DM + kb * 64 + 8 * kc) = o; }
	s_mov_b32 s99, 0x42fe0000
	s_add_u32 s74, s81, 4
	v_lshrrev_b32_e32 v252, 4, v89
	v_lshlrev_b32_e32 v252, s74, v252
	v_cmp_gt_u32_e32 vcc, 16, v0
	s_and_saveexec_b64 s[100:101], vcc
	v_mul_f32_e32 v224, 0x3c010204, v92
	v_mul_f32_e32 v225, 0x3c010204, v93
	v_mul_f32_e32 v226, 0x3c010204, v94
	v_mul_f32_e32 v227, 0x3c010204, v95
	s_lshl_b32 s75, 0, s81
	v_add_u32_e32 v253, s75, v252
	global_store_dword v253, v224, s[72:73]
	s_lshl_b32 s75, 4, s81
	v_add_u32_e32 v253, s75, v252
	global_store_dword v253, v225, s[72:73]
	s_lshl_b32 s75, 8, s81
	v_add_u32_e32 v253, s75, v252
	global_store_dword v253, v226, s[72:73]
	s_lshl_b32 s75, 12, s81
	v_add_u32_e32 v253, s75, v252
	global_store_dword v253, v227, s[72:73]
	s_mov_b64 exec, s[100:101]
	v_div_scale_f32 v244, s[74:75], v92, v92, s99
	v_rcp_f32_e32 v245, v244
	s_nop 0
	v_fma_f32 v246, -v244, v245, 1.0
	v_fmac_f32_e32 v245, v246, v245
	v_div_scale_f32 v246, vcc, s99, v92, s99
	v_mul_f32_e32 v247, v246, v245
	v_fma_f32 v252, -v244, v247, v246
	v_fmac_f32_e32 v247, v252, v245
	v_fma_f32 v244, -v244, v247, v246
	s_nop 0
	v_div_fmas_f32 v244, v244, v245, v247
	v_div_fixup_f32 v244, v244, v92, s99
	v_cmp_lt_f32_e32 vcc, 0, v92
	s_nop 1
	v_cndmask_b32_e32 v240, 0, v244, vcc
	v_div_scale_f32 v244, s[74:75], v93, v93, s99
	v_rcp_f32_e32 v245, v244
	s_nop 0
	v_fma_f32 v246, -v244, v245, 1.0
	v_fmac_f32_e32 v245, v246, v245
	v_div_scale_f32 v246, vcc, s99, v93, s99
	v_mul_f32_e32 v247, v246, v245
	v_fma_f32 v252, -v244, v247, v246
	v_fmac_f32_e32 v247, v252, v245
	v_fma_f32 v244, -v244, v247, v246
	s_nop 0
	v_div_fmas_f32 v244, v244, v245, v247
	v_div_fixup_f32 v244, v244, v93, s99
	v_cmp_lt_f32_e32 vcc, 0, v93
	s_nop 1
	v_cndmask_b32_e32 v241, 0, v244, vcc
	v_div_scale_f32 v244, s[74:75], v94, v94, s99
	v_rcp_f32_e32 v245, v244
	s_nop 0
	v_fma_f32 v246, -v244, v245, 1.0
	v_fmac_f32_e32 v245, v246, v245
	v_div_scale_f32 v246, vcc, s99, v94, s99
	v_mul_f32_e32 v247, v246, v245
	v_fma_f32 v252, -v244, v247, v246
	v_fmac_f32_e32 v247, v252, v245
	v_fma_f32 v244, -v244, v247, v246
	s_nop 0
	v_div_fmas_f32 v244, v244, v245, v247
	v_div_fixup_f32 v244, v244, v94, s99
	v_cmp_lt_f32_e32 vcc, 0, v94
	s_nop 1
	v_cndmask_b32_e32 v242, 0, v244, vcc
	v_div_scale_f32 v244, s[74:75], v95, v95, s99
	v_rcp_f32_e32 v245, v244
	s_nop 0
	v_fma_f32 v246, -v244, v245, 1.0
	v_fmac_f32_e32 v245, v246, v245
	v_div_scale_f32 v246, vcc, s99, v95, s99
	v_mul_f32_e32 v247, v246, v245
	v_fma_f32 v252, -v244, v247, v246
	v_fmac_f32_e32 v247, v252, v245
	v_fma_f32 v244, -v244, v247, v246
	s_nop 0
	v_div_fmas_f32 v244, v244, v245, v247
	v_div_fixup_f32 v244, v244, v95, s99
	v_cmp_lt_f32_e32 vcc, 0, v95
	s_nop 1
	v_cndmask_b32_e32 v243, 0, v244, vcc
	v_fmaak_f32 v96, v240, v96, 0x4b400000
	v_fmaak_f32 v100, v240, v100, 0x4b400000
	v_fmaak_f32 v104, v240, v104, 0x4b400000
	v_fmaak_f32 v108, v240, v108, 0x4b400000
	v_perm_b32 v252, v100, v96, s98
	v_perm_b32 v253, v108, v104, s98
	v_lshl_or_b32 v224, v253, 16, v252
	v_fmaak_f32 v112, v240, v112, 0x4b400000
	v_fmaak_f32 v116, v240, v116, 0x4b400000
	v_fmaak_f32 v120, v240, v120, 0x4b400000
	v_fmaak_f32 v124, v240, v124, 0x4b400000
	v_perm_b32 v252, v116, v112, s98
	v_perm_b32 v253, v124, v120, s98
	v_lshl_or_b32 v225, v253, 16, v252
	v_fmaak_f32 v128, v240, v128, 0x4b400000
	v_fmaak_f32 v132, v240, v132, 0x4b400000
	v_fmaak_f32 v136, v240, v136, 0x4b400000
	v_fmaak_f32 v140, v240, v140, 0x4b400000
	v_perm_b32 v252, v132, v128, s98
	v_perm_b32 v253, v140, v136, s98
	v_lshl_or_b32 v226, v253, 16, v252
	v_fmaak_f32 v144, v240, v144, 0x4b400000
	v_fmaak_f32 v148, v240, v148, 0x4b400000
	v_fmaak_f32 v152, v240, v152, 0x4b400000
	v_fmaak_f32 v156, v240, v156, 0x4b400000
	v_perm_b32 v252, v148, v144, s98
	v_perm_b32 v253, v156, v152, s98
	v_lshl_or_b32 v227, v253, 16, v252
	global_store_dwordx4 v248, v[224:227], s[70:71] offset:0
	v_fmaak_f32 v97, v241, v97, 0x4b400000
	v_fmaak_f32 v101, v241, v101, 0x4b400000
	v_fmaak_f32 v105, v241, v105, 0x4b400000
	v_fmaak_f32 v109, v241, v109, 0x4b400000
	v_perm_b32 v252, v101, v97, s98
	v_perm_b32 v253, v109, v105, s98
	v_lshl_or_b32 v228, v253, 16, v252
	v_fmaak_f32 v113, v241, v113, 0x4b400000
	v_fmaak_f32 v117, v241, v117, 0x4b400000
	v_fmaak_f32 v121, v241, v121, 0x4b400000
	v_fmaak_f32 v125, v241, v125, 0x4b400000
	v_perm_b32 v252, v117, v113, s98
	v_perm_b32 v253, v125, v121, s98
	v_lshl_or_b32 v229, v253, 16, v252
	v_fmaak_f32 v129, v241, v129, 0x4b400000
	v_fmaak_f32 v133, v241, v133, 0x4b400000
	v_fmaak_f32 v137, v241, v137, 0x4b400000
	v_fmaak_f32 v141, v241, v141, 0x4b400000
	v_perm_b32 v252, v133, v129, s98
	v_perm_b32 v253, v141, v137, s98
	v_lshl_or_b32 v230, v253, 16, v252
	v_fmaak_f32 v145, v241, v145, 0x4b400000
	v_fmaak_f32 v149, v241, v149, 0x4b400000
	v_fmaak_f32 v153, v241, v153, 0x4b400000
	v_fmaak_f32 v157, v241, v157, 0x4b400000
	v_perm_b32 v252, v149, v145, s98
	v_perm_b32 v253, v157, v153, s98
	v_lshl_or_b32 v231, v253, 16, v252
	global_store_dwordx4 v249, v[228:231], s[70:71] offset:0
	v_fmaak_f32 v98, v242, v98, 0x4b400000
	v_fmaak_f32 v102, v242, v102, 0x4b400000
	v_fmaak_f32 v106, v242, v106, 0x4b400000
	v_fmaak_f32 v110, v242, v110, 0x4b400000
	v_perm_b32 v252, v102, v98, s98
	v_perm_b32 v253, v110, v106, s98
	v_lshl_or_b32 v232, v253, 16, v252
	v_fmaak_f32 v114, v242, v114, 0x4b400000
	v_fmaak_f32 v118, v242, v118, 0x4b400000
	v_fmaak_f32 v122, v242, v122, 0x4b400000
	v_fmaak_f32 v126, v242, v126, 0x4b400000
	v_perm_b32 v252, v118, v114, s98
	v_perm_b32 v253, v126, v122, s98
	v_lshl_or_b32 v233, v253, 16, v252
	v_fmaak_f32 v130, v242, v130, 0x4b400000
	v_fmaak_f32 v134, v242, v134, 0x4b400000
	v_fmaak_f32 v138, v242, v138, 0x4b400000
; __device__ __forceinline__ void convert_i8_strip(const float* W, int ldw, signed char* WT, float* SWp, float* scr, int rmul, int radd) {
;     ...
;     for (int kb = 0; kb < 16; ++kb) {
; #pragma unroll
;         for (int i = 0; i < 8; ++i) scr[1024 + (kg + 8 * i) * 65 + nn] = r[i] * inv + 12582912.0f;
;         __syncthreads();
;         if (kb + 1 < 16) {
; #pragma unroll
;             for (int i = 0; i < 8; ++i) r[i] = W[(size_t)((kb + 1) * 64 + kg + 8 * i) * ldw + nn]; }
;         { const int on = t >> 3, kc = t & 7;
;           const unsigned* sp = (const unsigned*)(scr + 1024 + (8 * kc) * 65 + on);
;           u32x2 o; o.x = (sp[0] & 0xffu) | ((sp[65] & 0xffu) << 8) | ((sp[2 * 65] & 0xffu) << 16) | (sp[3 * 65] << 24);
;           o.y = (sp[4 * 65] & 0xffu) | ((sp[5 * 65] & 0xffu) << 8) | ((sp[6 * 65] & 0xffu) << 16) | (sp[7 * 65] << 24);
;           *(u32x2*)(WT + (ptrdiff_t)(rmul * on + radd) * DM + kb * 64 + 8 * kc) = o; }
;         __syncthreads();
	v_fmaak_f32 v142, v242, v142, 0x4b400000
	v_perm_b32 v252, v134, v130, s98
	v_perm_b32 v253, v142, v138, s98
	v_lshl_or_b32 v234, v253, 16, v252
	v_fmaak_f32 v146, v242, v146, 0x4b400000
	v_fmaak_f32 v150, v242, v150, 0x4b400000
	v_fmaak_f32 v154, v242, v154, 0x4b400000
	v_fmaak_f32 v158, v242, v158, 0x4b400000
	v_perm_b32 v252, v150, v146, s98
	v_perm_b32 v253, v158, v154, s98
	v_lshl_or_b32 v235, v253, 16, v252
	global_store_dwordx4 v250, v[232:235], s[70:71] offset:0
	v_fmaak_f32 v99, v243, v99, 0x4b400000
	v_fmaak_f32 v103, v243, v103, 0x4b400000
	v_fmaak_f32 v107, v243, v107, 0x4b400000
	v_fmaak_f32 v111, v243, v111, 0x4b400000
	v_perm_b32 v252, v103, v99, s98
	v_perm_b32 v253, v111, v107, s98
	v_lshl_or_b32 v236, v253, 16, v252
	v_fmaak_f32 v115, v243, v115, 0x4b400000
	v_fmaak_f32 v119, v243, v119, 0x4b400000
	v_fmaak_f32 v123, v243, v123, 0x4b400000
	v_fmaak_f32 v127, v243, v127, 0x4b400000
	v_perm_b32 v252, v119, v115, s98
	v_perm_b32 v253, v127, v123, s98
	v_lshl_or_b32 v237, v253, 16, v252
	v_fmaak_f32 v131, v243, v131, 0x4b400000
	v_fmaak_f32 v135, v243, v135, 0x4b400000
	v_fmaak_f32 v139, v243, v139, 0x4b400000
	v_fmaak_f32 v143, v243, v143, 0x4b400000
	v_perm_b32 v252, v135, v131, s98
	v_perm_b32 v253, v143, v139, s98
	v_lshl_or_b32 v238, v253, 16, v252
	v_fmaak_f32 v147, v243, v147, 0x4b400000
	v_fmaak_f32 v151, v243, v151, 0x4b400000
	v_fmaak_f32 v155, v243, v155, 0x4b400000
	v_fmaak_f32 v159, v243, v159, 0x4b400000
	v_perm_b32 v252, v151, v147, s98
	v_perm_b32 v253, v159, v155, s98
	v_lshl_or_b32 v239, v253, 16, v252
	global_store_dwordx4 v251, v[236:239], s[70:71] offset:0
	s_nop 1
	v_fmaak_f32 v160, v240, v160, 0x4b400000
	v_fmaak_f32 v164, v240, v164, 0x4b400000
	v_fmaak_f32 v168, v240, v168, 0x4b400000
	v_fmaak_f32 v172, v240, v172, 0x4b400000
	v_perm_b32 v252, v164, v160, s98
	v_perm_b32 v253, v172, v168, s98
	v_lshl_or_b32 v224, v253, 16, v252
	v_fmaak_f32 v176, v240, v176, 0x4b400000
	v_fmaak_f32 v180, v240, v180, 0x4b400000
	v_fmaak_f32 v184, v240, v184, 0x4b400000
	v_fmaak_f32 v188, v240, v188, 0x4b400000
	v_perm_b32 v252, v180, v176, s98
	v_perm_b32 v253, v188, v184, s98
	v_lshl_or_b32 v225, v253, 16, v252
	v_fmaak_f32 v192, v240, v192, 0x4b400000
	v_fmaak_f32 v196, v240, v196, 0x4b400000
	v_fmaak_f32 v200, v240, v200, 0x4b400000
	v_fmaak_f32 v204, v240, v204, 0x4b400000
	v_perm_b32 v252, v196, v192, s98
	v_perm_b32 v253, v204, v200, s98
	v_lshl_or_b32 v226, v253, 16, v252
	v_fmaak_f32 v208, v240, v208, 0x4b400000
	v_fmaak_f32 v212, v240, v212, 0x4b400000
	v_fmaak_f32 v216, v240, v216, 0x4b400000
	v_fmaak_f32 v220, v240, v220, 0x4b400000
	v_perm_b32 v252, v212, v208, s98
	v_perm_b32 v253, v220, v216, s98
	v_lshl_or_b32 v227, v253, 16, v252
	global_store_dwordx4 v248, v[224:227], s[70:71] offset:16
	v_fmaak_f32 v161, v241, v161, 0x4b400000
	v_fmaak_f32 v165, v241, v165, 0x4b400000
	v_fmaak_f32 v169, v241, v169, 0x4b400000
	v_fmaak_f32 v173, v241, v173, 0x4b400000
	v_perm_b32 v252, v165, v161, s98
	v_perm_b32 v253, v173, v169, s98
	v_lshl_or_b32 v228, v253, 16, v252
	v_fmaak_f32 v177, v241, v177, 0x4b400000
	v_fmaak_f32 v181, v241, v181, 0x4b400000
	v_fmaak_f32 v185, v241, v185, 0x4b400000
	v_fmaak_f32 v189, v241, v189, 0x4b400000
	v_perm_b32 v252, v181, v177, s98
	v_perm_b32 v253, v189, v185, s98
	v_lshl_or_b32 v229, v253, 16, v252
	v_fmaak_f32 v193, v241, v193, 0x4b400000
	v_fmaak_f32 v197, v241, v197, 0x4b400000
	v_fmaak_f32 v201, v241, v201, 0x4b400000
	v_fmaak_f32 v205, v241, v205, 0x4b400000
	v_perm_b32 v252, v197, v193, s98
	v_perm_b32 v253, v205, v201, s98
	v_lshl_or_b32 v230, v253, 16, v252
	v_fmaak_f32 v209, v241, v209, 0x4b400000
	v_fmaak_f32 v213, v241, v213, 0x4b400000
	v_fmaak_f32 v217, v241, v217, 0x4b400000
	v_fmaak_f32 v221, v241, v221, 0x4b400000
	v_perm_b32 v252, v213, v209, s98
	v_perm_b32 v253, v221, v217, s98
	v_lshl_or_b32 v231, v253, 16, v252
	global_store_dwordx4 v249, v[228:231], s[70:71] offset:16
	v_fmaak_f32 v162, v242, v162, 0x4b400000
	v_fmaak_f32 v166, v242, v166, 0x4b400000
	v_fmaak_f32 v170, v242, v170, 0x4b400000
	v_fmaak_f32 v174, v242, v174, 0x4b400000
	v_perm_b32 v252, v166, v162, s98
	v_perm_b32 v253, v174, v170, s98
	v_lshl_or_b32 v232, v253, 16, v252
	v_fmaak_f32 v178, v242, v178, 0x4b400000
	v_fmaak_f32 v182, v242, v182, 0x4b400000
	v_fmaak_f32 v186, v242, v186, 0x4b400000
	v_fmaak_f32 v190, v242, v190, 0x4b400000
	v_perm_b32 v252, v182, v178, s98
	v_perm_b32 v253, v190, v186, s98
	v_lshl_or_b32 v233, v253, 16, v252
	v_fmaak_f32 v194, v242, v194, 0x4b400000
	v_fmaak_f32 v198, v242, v198, 0x4b400000
	v_fmaak_f32 v202, v242, v202, 0x4b400000
	v_fmaak_f32 v206, v242, v206, 0x4b400000
	v_perm_b32 v252, v198, v194, s98
	v_perm_b32 v253, v206, v202, s98
	v_lshl_or_b32 v234, v253, 16, v252
	v_fmaak_f32 v210, v242, v210, 0x4b400000
	v_fmaak_f32 v214, v242, v214, 0x4b400000
	v_fmaak_f32 v218, v242, v218, 0x4b400000
	v_fmaak_f32 v222, v242, v222, 0x4b400000
	v_perm_b32 v252, v214, v210, s98
	v_perm_b32 v253, v222, v218, s98
	v_lshl_or_b32 v235, v253, 16, v252
	global_store_dwordx4 v250, v[232:235], s[70:71] offset:16
	v_fmaak_f32 v163, v243, v163, 0x4b400000
	v_fmaak_f32 v167, v243, v167, 0x4b400000
	v_fmaak_f32 v171, v243, v171, 0x4b400000
	v_fmaak_f32 v175, v243, v175, 0x4b400000
	v_perm_b32 v252, v167, v163, s98
	v_perm_b32 v253, v175, v171, s98
	v_lshl_or_b32 v236, v253, 16, v252
	v_fmaak_f32 v179, v243, v179, 0x4b400000
	v_fmaak_f32 v183, v243, v183, 0x4b400000
	v_fmaak_f32 v187, v243, v187, 0x4b400000
	v_fmaak_f32 v191, v243, v191, 0x4b400000
	v_perm_b32 v252, v183, v179, s98
	v_perm_b32 v253, v191, v187, s98
	v_lshl_or_b32 v237, v253, 16, v252
	v_fmaak_f32 v195, v243, v195, 0x4b400000
	v_fmaak_f32 v199, v243, v199, 0x4b400000
	v_fmaak_f32 v203, v243, v203, 0x4b400000
	v_fmaak_f32 v207, v243, v207, 0x4b400000
	v_perm_b32 v252, v199, v195, s98
	v_perm_b32 v253, v207, v203, s98
	v_lshl_or_b32 v238, v253, 16, v252
	v_fmaak_f32 v211, v243, v211, 0x4b400000
	v_fmaak_f32 v215, v243, v215, 0x4b400000
	v_fmaak_f32 v219, v243, v219, 0x4b400000
	v_fmaak_f32 v223, v243, v223, 0x4b400000
	v_perm_b32 v252, v215, v211, s98
	v_perm_b32 v253, v223, v219, s98
	v_lshl_or_b32 v239, v253, 16, v252
	global_store_dwordx4 v251, v[236:239], s[70:71] offset:16
	s_branch .LBB0_8
	s_nop 0
	s_nop 0
	s_nop 0
	s_nop 0
	s_nop 0
	s_nop 0
	s_nop 0
	s_nop 0
	s_nop 0
	s_nop 0
	s_nop 0
	s_nop 0
	s_nop 0
	s_nop 0
	s_nop 0
	s_nop 0
	s_nop 0
	s_nop 0
	s_nop 0
	s_nop 0
	s_nop 0
	s_nop 0
	s_nop 0
	s_nop 0
	s_nop 0
	s_nop 0
	s_nop 0
	s_nop 0
	s_nop 0
	s_nop 0
	s_nop 0
	s_nop 0
	s_nop 0
	s_nop 0
	s_nop 0
	s_nop 0
	s_nop 0
	s_nop 0
	s_nop 0
	s_nop 0
	s_nop 0
	s_nop 0
	s_nop 0
; #define TIDX opq((int)threadIdx.x)
; #define BIDX opqs((int)blockIdx.x)
; __device__ __forceinline__ void phase_pre(const Ctx& c, float* lds) {
;     ...
;     const int gt = BIDX * NTHREADS + TIDX, NT = gridDim.x * NTHREADS;
;     for (int i = gt; i < DEPTH * MT; i += NT) c.SS[i] = 0.f;
.LBB0_30:
	s_mov_b32 s2, s88
	v_mov_b32_e32 v1, v0
	s_load_dword s0, s[12:13], 0x10
	s_load_dword s20, s[12:13], 0x0
	v_lshl_add_u32 v2, s2, 9, v1
	s_waitcnt lgkmcnt(0)
	s_lshr_b32 s0, s0, 16
	s_cmp_lg_u32 s0, 0
	s_cselect_b64 s[0:1], -1, 0
	s_cmp_lg_u64 s[0:1], 0
	s_addc_u32 s18, s20, 0
	s_lshl_b32 s0, s18, 9
	v_cvt_f32_u32_e32 v3, s0
	s_mov_b32 s1, 0x10000
	v_cmp_gt_i32_e32 vcc, s1, v2
	v_rcp_iflag_f32_e32 v8, v3
	v_add_u32_e32 v3, s0, v2
	s_and_saveexec_b64 s[2:3], vcc
	s_cbranch_execz .LBB0_38
	v_mul_f32_e32 v6, 0x4f7ffffe, v8
	v_cvt_u32_f32_e32 v6, v6
	v_mov_b32_e32 v5, s0
	v_cmp_gt_i32_e32 vcc, s1, v3
	v_max_i32_e32 v4, 0x10000, v3
	s_sub_i32 s1, 0, s0
	v_addc_co_u32_e64 v5, s[4:5], v2, v5, vcc
	v_sub_u32_e32 v4, v4, v5
	v_mul_lo_u32 v5, s1, v6
	v_mul_hi_u32 v5, v6, v5
	v_add_u32_e32 v5, v6, v5
	v_mul_hi_u32 v5, v4, v5
	v_mul_lo_u32 v6, v5, s0
	v_sub_u32_e32 v4, v4, v6
	v_add_u32_e32 v6, 1, v5
	v_cmp_le_u32_e64 s[4:5], s0, v4
	s_mov_b64 s[14:15], -1
	s_nop 0
	v_cndmask_b32_e64 v5, v5, v6, s[4:5]
	v_subrev_u32_e32 v6, s0, v4
	v_cndmask_b32_e64 v4, v4, v6, s[4:5]
	v_add_u32_e32 v6, 1, v5
	v_cmp_le_u32_e64 s[4:5], s0, v4
	s_nop 1
	v_cndmask_b32_e64 v4, v5, v6, s[4:5]
	v_addc_co_u32_e32 v6, vcc, 1, v4, vcc
	v_cmp_lt_u32_e32 vcc, 1, v6
	v_mov_b32_e32 v4, v2
	s_and_saveexec_b64 s[4:5], vcc
	s_cbranch_execz .LBB0_35
	s_add_u32 s14, s6, 0x1dca8000
	s_addc_u32 s15, s7, 0
	v_and_b32_e32 v7, -2, v6
	s_lshl_b32 s1, s18, 10
	s_mov_b32 s19, s1
	s_mov_b64 s[16:17], 0
	v_mov_b32_e32 v9, 0
	v_mov_b32_e32 v10, v7
	v_mov_b64_e32 v[4:5], v[2:3]
	s_waitcnt vmcnt(0)

; #define BIDX opqs((int)blockIdx.x)
; template <int L, int Q>
; __device__ __forceinline__ void layer_phase(unsigned char* lds_raw) {
;     ...
;             const int G_ = (int)gridDim.x, c_ = BIDX, nfull = (MT / 256) * (DIN / 256) % G_;
;             const int nidle = (nfull == 0) ? G_ : G_ - nfull, j_ = (nfull == 0) ? c_ : c_ - nfull;
;             constexpr int g_lo = (l == 0) ? TR_WIN : TR_PER_LAYER + TR_WIN, g_hi = (l == 0) ? TR_PER_LAYER : 2 * TR_PER_LAYER;
;             constexpr int nstrips = (l == 0) ? 64 + DIN / 64 : 64;
;             if (l < 2 && j_ >= 0) {
;                 for (int s_ = j_; s_ < nstrips; s_ += nidle) { if (s_ < 64) convert_strip(c, (float*)lds_raw, l, s_); else convert_strip(c, (float*)lds_raw, 1, s_); }
;                 const int jf = (nstrips % nidle == 0 || nstrips % nidle > nidle - 8) ? 0 : nstrips % nidle;
;                 if (j_ >= jf) convert_items(c, (float*)lds_raw, g_lo, g_hi, j_ - jf, nidle - jf);
.LBB0_208:
	s_waitcnt lgkmcnt(0)
	s_abs_i32 s1, s58
	v_cvt_f32_u32_e32 v1, s1
	s_sub_i32 s2, 0, s1
	s_mov_b32 s0, s88
	v_rcp_iflag_f32_e32 v1, v1
	s_nop 0
	v_mul_f32_e32 v1, 0x4f7ffffe, v1
	v_cvt_u32_f32_e32 v1, v1
	s_nop 0
	v_readfirstlane_b32 s3, v1
	s_mul_i32 s2, s2, s3
	s_mul_hi_u32 s2, s3, s2
	s_add_i32 s3, s3, s2
	s_mul_hi_u32 s2, s3, 0x880
	s_mul_i32 s2, s2, s1
	s_sub_i32 s2, 0x880, s2
	s_sub_i32 s3, s2, s1
	s_cmp_ge_u32 s2, s1
	s_cselect_b32 s2, s3, s2
	s_sub_i32 s3, s2, s1
	s_cmp_ge_u32 s2, s1
	s_cselect_b32 s1, s3, s2
	s_sub_i32 s34, s0, s1
	s_cmp_lt_i32 s34, 0
	s_cbranch_scc1 .LBB0_281
	s_sub_i32 s33, s58, s1
	s_cmpk_gt_u32 s34, 0x3f
	s_cbranch_scc1 .LBB0_233
	s_add_u32 s35, s24, 0x1dd28000
	s_addc_u32 s36, s25, 0
	s_add_u32 s37, s8, 0x1100000
	s_addc_u32 s38, s9, 0
	s_add_u32 s39, s24, 0x1dd34400
	s_addc_u32 s40, s25, 0
	s_add_u32 s4, s24, 0xcd0000
	s_addc_u32 s5, s25, 0
	s_lshl_b32 s0, s0, 6
	s_lshl_b32 s1, s1, 6
	s_sub_i32 s41, s0, s1
	s_lshl_b32 s0, s58, 6
	s_add_i32 s6, s41, 0xfffff000
	s_sub_i32 s42, s0, s1
	s_add_u32 s26, s24, 0x1110000
	s_addc_u32 s27, s25, 0
	s_mov_b32 s7, 0
	v_mov_b32_e32 v3, 0
	s_movk_i32 s43, 0x4400
	s_mov_b32 s44, 0x42fe0000
	s_movk_i32 s45, 0x104
	s_mov_b32 s46, 0xc0c0500
	s_mov_b32 s47, s34
	s_branch .LBB0_212
.LBB0_211:
	s_add_i32 s47, s47, s33
	s_add_i32 s6, s6, s42
	s_add_i32 s41, s41, s42
	s_cmpk_gt_i32 s47, 0x3f
	s_cbranch_scc1 .LBB0_233

; #define BIDX opqs((int)blockIdx.x)
; template <int L, int Q>
; __device__ __forceinline__ void layer_phase(unsigned char* lds_raw) {
;     ...
;             const int G_ = (int)gridDim.x, c_ = BIDX, nfull = (MT / 256) * (DIN / 256) % G_;
;             const int nidle = (nfull == 0) ? G_ : G_ - nfull, j_ = (nfull == 0) ? c_ : c_ - nfull;
;             constexpr int g_lo = (l == 0) ? TR_WIN : TR_PER_LAYER + TR_WIN, g_hi = (l == 0) ? TR_PER_LAYER : 2 * TR_PER_LAYER;
;             constexpr int nstrips = (l == 0) ? 64 + DIN / 64 : 64;
;             if (l < 2 && j_ >= 0) {
;                 for (int s_ = j_; s_ < nstrips; s_ += nidle) { if (s_ < 64) convert_strip(c, (float*)lds_raw, l, s_); else convert_strip(c, (float*)lds_raw, 1, s_); }
;                 const int jf = (nstrips % nidle == 0 || nstrips % nidle > nidle - 8) ? 0 : nstrips % nidle;
;                 if (j_ >= jf) convert_items(c, (float*)lds_raw, g_lo, g_hi, j_ - jf, nidle - jf);
.LBB0_233:
	s_abs_i32 s0, s33
	v_cvt_f32_u32_e32 v1, s0
	s_sub_i32 s1, 0, s0
	v_rcp_iflag_f32_e32 v1, v1
	s_nop 0
	v_mul_f32_e32 v1, 0x4f7ffffe, v1
	v_cvt_u32_f32_e32 v1, v1
	s_nop 0
	v_readfirstlane_b32 s2, v1
	s_mul_i32 s1, s1, s2
	s_mul_hi_u32 s1, s2, s1
	s_add_i32 s2, s2, s1
	s_mul_hi_u32 s1, s2, 64
	s_mul_i32 s1, s1, s0
	s_sub_i32 s1, 64, s1
	s_sub_i32 s2, s1, s0
	s_cmp_ge_u32 s1, s0
	s_cselect_b32 s1, s2, s1
	s_sub_i32 s2, s1, s0
	s_cmp_ge_u32 s1, s0
	s_cselect_b32 s4, s2, s1
	s_cmp_eq_u32 s4, 0
	s_cselect_b64 s[0:1], -1, 0
	s_add_i32 s2, s33, -8
	s_cmp_gt_i32 s4, s2
	s_cselect_b64 s[2:3], -1, 0
	s_or_b64 s[0:1], s[0:1], s[2:3]
	s_and_b64 s[0:1], s[0:1], exec
	s_cselect_b32 s28, 0, s4
	s_cmp_ge_i32 s34, s28
	s_cbranch_scc0 .LBB0_281
	s_sub_i32 s29, s34, s28
	v_mov_b32_e32 v4, v0
	s_cmpk_gt_u32 s29, 0x223
	s_cbranch_scc1 .LBB0_281
	s_add_u32 s34, s24, 0x2110000
	s_addc_u32 s35, s25, 0
	s_add_u32 s0, s24, 0x2510000
	s_addc_u32 s1, s25, 0
	s_add_u32 s4, s24, 0x2910000
	s_addc_u32 s5, s25, 0
	s_add_u32 s6, s24, 0x2950000
	s_addc_u32 s7, s25, 0
	s_add_u32 s36, s24, 0x2990000
	s_addc_u32 s37, s25, 0
	s_cmpk_gt_u32 s29, 0xff
	s_cbranch_scc0 .LBB0_240
	s_cmpk_gt_u32 s29, 0x1ff
	s_cbranch_scc0 .LBB0_241
	s_cmpk_gt_u32 s29, 0x20f
	s_cbranch_scc0 .LBB0_242
	s_cmpk_gt_u32 s29, 0x21f
	s_cbranch_scc0 .LBB0_243
	s_add_i32 s18, s29, 0xfffffde0
	s_mov_b32 s19, 0
	s_lshl_b64 s[2:3], s[18:19], 14
	s_add_u32 s2, s14, s2
	s_addc_u32 s3, s15, s3
	s_lshl_b64 s[18:19], s[18:19], 13
	s_add_u32 s18, s36, s18
	s_addc_u32 s19, s37, s19
	s_mov_b64 s[26:27], 0
	s_branch .LBB0_244
